# v14 plus DSA loop: next-tile loads moved after the first K-fragment LDS reads and converted to HBM->LDS direct loads (mask word stays a register load)
# speedup vs baseline: 1.0096x; 1.0096x over previous
; #define LAS __attribute__((address_space(3)))
; __device__ __forceinline__ void mask_bits(f32x16& p0, f32x16& p1, unsigned lo, unsigned hi_w, int hi) {
;     const unsigned a = lo >> (4 * hi), b = hi_w >> (4 * hi); const unsigned NEGB = 0xFF800000u;
; #pragma unroll
;     for (int r = 0; r < 16; ++r) { const int c = (r & 3) + 8 * (r >> 2);
;         const unsigned ma = (unsigned)__builtin_amdgcn_sbfe((int)a, c, 1), mb = (unsigned)__builtin_amdgcn_sbfe((int)b, c, 1);
;         const float x0 = p0[r], x1 = p1[r];
;         p0[r] = __uint_as_float((__float_as_uint(x0) & ma) | (NEGB & ~ma));
;         p1[r] = __uint_as_float((__float_as_uint(x1) & mb) | (NEGB & ~mb)); }
; }
; __device__ __forceinline__ float max3f(float a, float b, float c) { return __builtin_fmaxf(__builtin_fmaxf(a, b), c); }
; __device__ __forceinline__ void partialSM(f32x16& p0, f32x16& p1, float& m_reg, float& mn, float& alpha, const float sc, const float C2) {
;     float pmax = max3f(p0[0], p0[1], p0[2]);
; #pragma unroll
;     for (int r = 3; r < 15; r += 2) pmax = max3f(pmax, p0[r], p0[r + 1]);
;     pmax = max3f(pmax, p0[15], p1[0]);
; #pragma unroll
;     for (int r = 1; r < 15; r += 2) pmax = max3f(pmax, p1[r], p1[r + 1]);
;     pmax = fmaxf(pmax, p1[15]);
;     { auto rr = __builtin_amdgcn_permlane32_swap(__float_as_uint(pmax), __float_as_uint(pmax), false, false);
;       pmax = fmaxf(__uint_as_float(rr[0]), __uint_as_float(rr[1])); }
; template <bool MLA>
; __device__ __forceinline__ void qkt2(f32x16& p0, f32x16& p1, const LAS char* lds, int kboff, int kroff, int r32, int hi, const half8* qr) {
;     const LAS char* kb[4];
; #pragma unroll
;     for (int dd = 0; dd < 4; ++dd) kb[dd] = lds + OFF_K + kboff + FA_KSWZ(r32, (dd * 16 + hi * 8) * 2);
;     constexpr int NG = MLA ? 6 : 4;
;     half8 fa0[2], fa1[2], fb0[2], fb1[2];
;     ...
; #pragma unroll
;     for (int r = 0; r < 16; ++r) { p0[r] = 0.f; p1[r] = 0.f; }
;     QK_LD(fa0, fa1, 0); FA_SBAR();
;     QK_LD(fb0, fb1, 1); FA_SBAR(); QK_MM(fa0, fa1, 0); FA_SBAR();
;     QK_LD(fa0, fa1, 2); FA_SBAR(); QK_MM(fb0, fb1, 1); FA_SBAR();
;     QK_LD(fb0, fb1, 3); FA_SBAR(); QK_MM(fa0, fa1, 2); FA_SBAR();
;     if constexpr (NG == 6) {
;         QK_LD(fa0, fa1, 4); FA_SBAR(); QK_MM(fb0, fb1, 3); FA_SBAR();
;         QK_LD(fb0, fb1, 5); FA_SBAR(); QK_MM(fa0, fa1, 4); FA_SBAR();
;         QK_MM(fb0, fb1, 5);
;     } else QK_MM(fb0, fb1, 3);
.LBB0_4934:
	s_and_b32 s8, s24, 1
	v_mov_b32_e32 v2, s8
	s_cmp_gt_i32 s22, s17
	s_cbranch_scc1 .Ldsa_skipq
	v_lshlrev_b32_e32 v2, 14, v2
	v_add_u32_e32 v6, v180, v2
	v_add_u32_e32 v196, v6, v181
	v_add_u32_e32 v197, v6, v182
	v_add_u32_e32 v208, v6, v183
	v_add_u32_e32 v209, v6, v184
	ds_read_b128 v[6:9], v196 offset:32768
	ds_read_b128 v[10:13], v196 offset:40960
	ds_read_b128 v[14:17], v197 offset:32768
	ds_read_b128 v[188:191], v197 offset:40960
	ds_read_b128 v[192:195], v208 offset:32768
	ds_read_b128 v[204:207], v208 offset:40960
	ds_read_b128 v[220:223], v209 offset:32768
	ds_read_b128 v[224:227], v209 offset:40960
	s_and_b64 vcc, exec, s[6:7]
	s_cbranch_vccz .Ldsa_q_nold
	v_readfirstlane_b32 vcc_hi, v0
	s_and_b32 vcc_lo, s23, 0x4000
	s_lshr_b32 vcc_hi, vcc_hi, 6
	s_lshl_b32 vcc_hi, vcc_hi, 10
	s_add_i32 vcc_lo, vcc_lo, vcc_hi
	v_add_u32_e32 v98, s22, v162
	v_add_u32_e32 v100, 64, v98
	v_ashrrev_i32_e32 v101, 31, v100
	v_add_u32_e32 v104, 0x60, v98
	v_lshlrev_b64 v[100:101], 8, v[100:101]
	v_ashrrev_i32_e32 v105, 31, v104
	s_add_i32 m0, vcc_lo, 0x8000
	v_lshl_add_u64 v[102:103], v[166:167], 0, v[100:101]
	v_lshlrev_b64 v[104:105], 8, v[104:105]
	global_load_lds_dwordx4 v[102:103], off
	s_add_i32 m0, vcc_lo, 0xa000
	v_lshl_add_u64 v[106:107], v[166:167], 0, v[104:105]
	v_lshl_add_u64 v[100:101], v[168:169], 0, v[100:101]
	global_load_lds_dwordx4 v[106:107], off
	s_mov_b32 m0, vcc_lo
	v_lshl_add_u64 v[102:103], v[168:169], 0, v[104:105]
	s_nop 0
	global_load_lds_dwordx4 v[100:101], off
	s_add_i32 m0, vcc_lo, 0x2000
	s_nop 0
	global_load_lds_dwordx4 v[102:103], off
	s_nop 0
	global_load_dwordx2 v[4:5], v[170:171], off
.Ldsa_q_nold:
	s_waitcnt lgkmcnt(7)
	v_mfma_f32_32x32x16_f16 v[82:97], v[6:9], v[130:133], 0
	s_waitcnt lgkmcnt(6)
	v_mfma_f32_32x32x16_f16 v[98:113], v[10:13], v[130:133], 0
	s_waitcnt lgkmcnt(5)
	v_mfma_f32_32x32x16_f16 v[82:97], v[14:17], v[134:137], v[82:97]
	s_waitcnt lgkmcnt(4)
	v_mfma_f32_32x32x16_f16 v[98:113], v[188:191], v[134:137], v[98:113]
	ds_read_b128 v[6:9], v196 offset:32896
	ds_read_b128 v[10:13], v196 offset:41088
	ds_read_b128 v[14:17], v197 offset:32896
	ds_read_b128 v[188:191], v197 offset:41088
	s_waitcnt lgkmcnt(7)
	v_mfma_f32_32x32x16_f16 v[82:97], v[192:195], v[138:141], v[82:97]
	s_waitcnt lgkmcnt(6)
	v_mfma_f32_32x32x16_f16 v[98:113], v[204:207], v[138:141], v[98:113]
	s_waitcnt lgkmcnt(5)
	v_mfma_f32_32x32x16_f16 v[82:97], v[220:223], v[142:145], v[82:97]
	s_waitcnt lgkmcnt(4)
	v_mfma_f32_32x32x16_f16 v[98:113], v[224:227], v[142:145], v[98:113]
	ds_read_b128 v[192:195], v208 offset:32896
	ds_read_b128 v[204:207], v208 offset:41088
	ds_read_b128 v[220:223], v209 offset:32896
	ds_read_b128 v[224:227], v209 offset:41088
	s_waitcnt lgkmcnt(7)
	v_mfma_f32_32x32x16_f16 v[82:97], v[6:9], v[146:149], v[82:97]
	s_waitcnt lgkmcnt(6)
	v_mfma_f32_32x32x16_f16 v[98:113], v[10:13], v[146:149], v[98:113]
	s_waitcnt lgkmcnt(5)
	v_mfma_f32_32x32x16_f16 v[82:97], v[14:17], v[150:153], v[82:97]
	s_waitcnt lgkmcnt(4)
	v_mfma_f32_32x32x16_f16 v[98:113], v[188:191], v[150:153], v[98:113]
	s_waitcnt lgkmcnt(3)
	v_mfma_f32_32x32x16_f16 v[82:97], v[192:195], v[154:157], v[82:97]
	v_lshrrev_b32_e32 v189, v174, v164
	v_lshrrev_b32_e32 v190, v174, v165
	v_bfe_i32 v6, v189, 0, 1
	v_bfe_i32 v7, v190, 0, 1
	v_bfe_i32 v8, v190, 1, 1
	v_bfe_i32 v9, v190, 2, 1
	v_bfe_i32 v10, v190, 3, 1
	s_waitcnt lgkmcnt(2)
	v_mfma_f32_32x32x16_f16 v[98:113], v[204:207], v[154:157], v[98:113]
	v_bfe_i32 v11, v190, 8, 1
	v_bfe_i32 v12, v190, 9, 1
	v_bfe_i32 v13, v190, 10, 1
	v_bfe_i32 v14, v190, 11, 1
	v_bfe_i32 v15, v190, 16, 1
	v_bfe_i32 v16, v190, 17, 1
	v_bfe_i32 v17, v190, 18, 1
	s_waitcnt lgkmcnt(1)
	v_mfma_f32_32x32x16_f16 v[82:97], v[220:223], v[158:161], v[82:97]
	s_waitcnt lgkmcnt(0)
	v_mfma_f32_32x32x16_f16 v[98:113], v[224:227], v[158:161], v[98:113]
	s_nop 9
	v_bitop3_b32 v188, v82, s36, v6 bitop3:0xe4
	v_bfe_i32 v82, v190, 19, 1
	v_bitop3_b32 v6, v98, s36, v7 bitop3:0xe4
	v_bfe_i32 v7, v189, 1, 1
	v_bitop3_b32 v98, v83, s36, v7 bitop3:0xe4
	v_bitop3_b32 v7, v99, s36, v8 bitop3:0xe4
	v_bfe_i32 v8, v189, 2, 1
	v_bitop3_b32 v99, v84, s36, v8 bitop3:0xe4
	v_bitop3_b32 v8, v100, s36, v9 bitop3:0xe4
	v_bfe_i32 v9, v189, 3, 1
	v_bitop3_b32 v100, v85, s36, v9 bitop3:0xe4
	v_bitop3_b32 v9, v101, s36, v10 bitop3:0xe4
	v_bfe_i32 v10, v189, 8, 1
	v_bitop3_b32 v101, v86, s36, v10 bitop3:0xe4
	v_bitop3_b32 v10, v102, s36, v11 bitop3:0xe4
	v_bfe_i32 v11, v189, 9, 1
	v_bitop3_b32 v87, v87, s36, v11 bitop3:0xe4
	v_bitop3_b32 v11, v103, s36, v12 bitop3:0xe4
	v_bfe_i32 v12, v189, 10, 1
	v_bitop3_b32 v88, v88, s36, v12 bitop3:0xe4
	v_bitop3_b32 v12, v104, s36, v13 bitop3:0xe4
	v_bfe_i32 v13, v189, 11, 1
	v_bitop3_b32 v89, v89, s36, v13 bitop3:0xe4
	v_bitop3_b32 v13, v105, s36, v14 bitop3:0xe4
	v_bfe_i32 v14, v189, 16, 1
	v_bitop3_b32 v90, v90, s36, v14 bitop3:0xe4
	v_bitop3_b32 v14, v106, s36, v15 bitop3:0xe4
	v_bfe_i32 v15, v189, 17, 1
	v_bitop3_b32 v91, v91, s36, v15 bitop3:0xe4
	v_bitop3_b32 v15, v107, s36, v16 bitop3:0xe4
	v_bfe_i32 v16, v189, 18, 1
	v_bitop3_b32 v92, v92, s36, v16 bitop3:0xe4
	v_bitop3_b32 v16, v108, s36, v17 bitop3:0xe4
	v_bfe_i32 v17, v189, 19, 1
	v_bitop3_b32 v93, v93, s36, v17 bitop3:0xe4
	v_bitop3_b32 v17, v109, s36, v82 bitop3:0xe4
	v_bfe_i32 v82, v189, 24, 1
	v_bfe_i32 v83, v190, 24, 1
	v_bitop3_b32 v94, v94, s36, v82 bitop3:0xe4
	v_bitop3_b32 v82, v110, s36, v83 bitop3:0xe4
	v_bfe_i32 v83, v189, 25, 1
	v_bfe_i32 v84, v190, 25, 1
	v_bitop3_b32 v95, v95, s36, v83 bitop3:0xe4
	v_bitop3_b32 v83, v111, s36, v84 bitop3:0xe4
	v_bfe_i32 v84, v189, 26, 1
	v_bfe_i32 v85, v190, 26, 1
	v_bitop3_b32 v96, v96, s36, v84 bitop3:0xe4
	v_bitop3_b32 v84, v112, s36, v85 bitop3:0xe4
	v_bfe_i32 v85, v189, 27, 1
	v_bfe_i32 v86, v190, 27, 1
	v_bitop3_b32 v97, v97, s36, v85 bitop3:0xe4
	v_bitop3_b32 v85, v113, s36, v86 bitop3:0xe4
	v_max_f32_e32 v86, v98, v98
	v_max_f32_e32 v102, v188, v188
	v_max_f32_e32 v86, v102, v86
	v_max3_f32 v86, v86, v99, v100
	v_max3_f32 v86, v86, v101, v87
	v_max3_f32 v86, v86, v88, v89
	v_max3_f32 v86, v86, v90, v91
	v_max3_f32 v86, v86, v92, v93
	v_max3_f32 v86, v86, v94, v95
	v_max3_f32 v86, v86, v96, v97
	v_max3_f32 v86, v86, v6, v7
	v_max3_f32 v86, v86, v8, v9
	v_max3_f32 v86, v86, v10, v11
	v_max3_f32 v86, v86, v12, v13
	v_max3_f32 v86, v86, v14, v15
	v_max3_f32 v86, v86, v16, v17
	v_max3_f32 v86, v86, v82, v83
	v_max3_f32 v86, v86, v84, v85
	v_mov_b32_e32 v102, v86
	s_nop 1
	v_permlane32_swap_b32_e32 v86, v102
	v_max_f32_e32 v86, v86, v102
	v_sub_f32_e32 v102, v86, v186
	v_mul_f32_e32 v103, 0x3db504f3, v102
	v_cmp_ge_f32_e32 vcc, s87, v103
	s_cmp_eq_u64 vcc, exec
	s_cbranch_scc0 .Ldsa_slow
	v_mov_b32_e32 v86, 1.0

; template <int KIND>
; __device__ __forceinline__ void run_unit(LAS char* lds, const UnitArgs& U, int tid_in) {
;     ...
;         if (t + 1 < NT) FA_LOADT(U.j_lo + t + 1);
.Ldsa_skipq:
	s_and_b64 vcc, exec, s[6:7]
	s_cbranch_vccz .LBB0_4940
	v_readfirstlane_b32 vcc_hi, v0
	s_and_b32 vcc_lo, s23, 0x4000
	s_lshr_b32 vcc_hi, vcc_hi, 6
	s_lshl_b32 vcc_hi, vcc_hi, 10
	s_add_i32 vcc_lo, vcc_lo, vcc_hi
	v_add_u32_e32 v2, s22, v162
	v_add_u32_e32 v4, 64, v2
	v_ashrrev_i32_e32 v5, 31, v4
	v_add_u32_e32 v8, 0x60, v2
	v_lshlrev_b64 v[4:5], 8, v[4:5]
	v_ashrrev_i32_e32 v9, 31, v8
	s_add_i32 m0, vcc_lo, 0x8000
	v_lshl_add_u64 v[6:7], v[166:167], 0, v[4:5]
	v_lshlrev_b64 v[8:9], 8, v[8:9]
	global_load_lds_dwordx4 v[6:7], off
	s_add_i32 m0, vcc_lo, 0xa000
	v_lshl_add_u64 v[10:11], v[166:167], 0, v[8:9]
	v_lshl_add_u64 v[4:5], v[168:169], 0, v[4:5]
	global_load_lds_dwordx4 v[10:11], off
	s_mov_b32 m0, vcc_lo
	v_lshl_add_u64 v[6:7], v[168:169], 0, v[8:9]
	s_nop 0
	global_load_lds_dwordx4 v[4:5], off
	s_add_i32 m0, vcc_lo, 0x2000
	s_nop 0
	global_load_lds_dwordx4 v[6:7], off
	s_nop 0
	global_load_dwordx2 v[4:5], v[170:171], off
	s_branch .LBB0_4940
